# P8: halves' epilogues un-aligned for units with a successor (align barrier only before the last unit's epilogue, restore barrier dropped) so the leading half's next-unit header, first load segment and
# baseline (speedup 1.0000x reference)
;     __device__ __forceinline__ void operator()(const f32x4 (&acc)[2][2][4][2], const Unit& u, int wr, int wc, int fr, int fq) const {
;         const int ch0 = u.pn * 128 + wc * 32 + 8 * fq;
;         f32x4 w0[2], w1[2], w2[2];
; #pragma unroll
;         for (int n = 0; n < 2; ++n) { w0[n] = *(const f32x4*)(cw + ch0 + 4 * n); w1[n] = *(const f32x4*)(cw + ldh + ch0 + 4 * n); w2[n] = *(const f32x4*)(cw + 2 * ldh + ch0 + 4 * n); }
;         const bool f1 = fr >= 1, f2 = fr >= 2;
; #pragma unroll
;         for (int ai = 0; ai < 2; ++ai) {
;             const int blk = u.pm * 4 + ai * 2 + wr;
; #pragma unroll
;             for (int m = 0; m < 4; ++m) {
;                 const size_t row = (size_t)(u.pm * BM + ai * HALF + wr * 64 + m * 16 + fr);
;                 float hg[8];
; #pragma unroll
;                 for (int n = 0; n < 2; ++n)
; #pragma unroll
;                     for (int i = 0; i < 4; ++i) {
;                         const float cur = acc[ai][0][m][n][i], prv = (m > 0) ? acc[ai][0][m > 0 ? m - 1 : 0][n][i] : cur;
;                         const float r1c = dpp_ror1(cur), r1p = dpp_ror1(prv), r2c = dpp_ror2(cur), r2p = dpp_ror2(prv);
;                         const float tm1 = f1 ? r1c : r1p, tm2 = f2 ? r2c : r2p;
;                         const float cv = w0[n][i] * tm2 + w1[n][i] * tm1 + w2[n][i] * cur;
;                         hg[4 * n + i] = cv * sigmoidf_(cv) * acc[ai][1][m][n][i];
;                     }
;                 if (m == 0 && fr < 2) {
;                     const f32x4 a0 = acc[ai][0][0][0], a1 = acc[ai][0][0][1], v0 = acc[ai][1][0][0], v1 = acc[ai][1][0][1];
;                     u32x4 wa, wv; wa.x = cvt_pk_bf16(a0[0], a0[1]); wa.y = cvt_pk_bf16(a0[2], a0[3]); wa.z = cvt_pk_bf16(a1[0], a1[1]); wa.w = cvt_pk_bf16(a1[2], a1[3]);
;                     wv.x = cvt_pk_bf16(v0[0], v0[1]); wv.y = cvt_pk_bf16(v0[2], v0[3]); wv.z = cvt_pk_bf16(v1[0], v1[1]); wv.w = cvt_pk_bf16(v1[2], v1[3]);
;                     *(u32x4*)(side + ((size_t)blk * 6 + 2 + fr) * ldh + ch0) = wa; *(u32x4*)(side + ((size_t)blk * 6 + 4 + fr) * ldh + ch0) = wv;
;                 } else {
;                     u32x4 w; w.x = cvt_pk_bf16(hg[0], hg[1]); w.y = cvt_pk_bf16(hg[2], hg[3]); w.z = cvt_pk_bf16(hg[4], hg[5]); w.w = cvt_pk_bf16(hg[6], hg[7]);
;                     *(u32x4*)(HG + row * ldh + ch0) = w;
.Lpeel_exit_3:
	s_and_b64 vcc, exec, s[54:55]
	s_cbranch_vccz .LBB0_713
	s_cmp_lg_u64 s[20:21], 0
	s_cbranch_scc1 .LBB0_713
	s_barrier
.LBB0_713:
	v_lshl_or_b32 v70, s15, 7, v221
	v_lshlrev_b32_e32 v71, 2, v70
	global_load_dwordx4 v[224:227], v71, s[52:53]
	global_load_dwordx4 v[228:231], v71, s[52:53] offset:16
	global_load_dwordx4 v[232:235], v71, s[56:57]
	global_load_dwordx4 v[236:239], v71, s[56:57] offset:16
	global_load_dwordx4 v[192:195], v71, s[58:59]
	global_load_dwordx4 v[196:199], v71, s[58:59] offset:16
	s_mov_b32 s65, 0x100000
	v_and_b32_e32 v72, 15, v161
	v_cmp_eq_u32_e64 s[16:17], 15, v72
	v_lshlrev_b32_e32 v188, 1, v70
	v_mov_b32_e32 v189, 0
	v_lshl_add_u32 v73, s14, 8, v161
	v_mad_u64_u32 v[170:171], vcc, v73, s92, v[188:189]
	s_lshl_b32 s14, s14, 2
	s_add_i32 s14, s14, s8
	s_mul_i32 s14, s14, 6
	v_add_u32_e32 v73, s14, v72
	v_lshl_add_u64 v[170:171], s[50:51], 0, v[170:171]
	v_mad_u64_u32 v[190:191], vcc, v73, s92, v[188:189]
	s_mov_b64 s[22:23], exec
	s_mov_b32 s14, 0xbfb8aa3b
	s_mov_b32 s15, 0xbfb8aa3b
	s_mov_b32 s24, 1.0
	s_mov_b32 s25, 1.0
	v_lshl_add_u64 v[190:191], s[48:49], 0, v[190:191]
	s_waitcnt vmcnt(0)
	v_cvt_pk_bf16_f32 v154, v142, v143
	v_cvt_pk_bf16_f32 v155, v144, v145
	v_cvt_pk_bf16_f32 v156, v130, v131
	v_cvt_pk_bf16_f32 v157, v132, v133
	v_cvt_pk_bf16_f32 v204, v150, v151
	v_cvt_pk_bf16_f32 v205, v152, v153
	v_cvt_pk_bf16_f32 v206, v146, v147
	v_cvt_pk_bf16_f32 v207, v148, v149
	v_add_co_u32_e32 v188, vcc, 0xac00, v190
	v_addc_co_u32_e32 v189, vcc, 0, v191, vcc
	v_add_co_u32_e32 v208, vcc, 0x15800, v190
	v_addc_co_u32_e32 v209, vcc, 0, v191, vcc
	s_andn2_b64 exec, s[22:23], s[40:41]
	global_store_dwordx4 v[188:189], v[154:157], off
	global_store_dwordx4 v[208:209], v[204:207], off
	s_mov_b64 exec, s[22:23]
	s_nop 4
	v_pk_mul_f32 v[70:71], v[192:193], v[142:143]
	v_pk_mul_f32 v[72:73], v[194:195], v[144:145]
	v_fmac_f32_dpp v70, v142, v232 row_ror:1 row_mask:0xf bank_mask:0xf
	v_fmac_f32_dpp v71, v143, v233 row_ror:1 row_mask:0xf bank_mask:0xf
	v_fmac_f32_dpp v72, v144, v234 row_ror:1 row_mask:0xf bank_mask:0xf
	v_fmac_f32_dpp v73, v145, v235 row_ror:1 row_mask:0xf bank_mask:0xf
	v_fmac_f32_dpp v70, v142, v224 row_ror:2 row_mask:0xf bank_mask:0xf
	v_fmac_f32_dpp v71, v143, v225 row_ror:2 row_mask:0xf bank_mask:0xf
	v_fmac_f32_dpp v72, v144, v226 row_ror:2 row_mask:0xf bank_mask:0xf
	v_fmac_f32_dpp v73, v145, v227 row_ror:2 row_mask:0xf bank_mask:0xf
	v_pk_mul_f32 v[200:201], v[70:71], s[14:15]
	v_pk_mul_f32 v[202:203], v[72:73], s[14:15]
	v_exp_f32_e32 v200, v200
	v_exp_f32_e32 v201, v201
	v_exp_f32_e32 v202, v202
	v_exp_f32_e32 v203, v203
	v_pk_add_f32 v[200:201], v[200:201], s[24:25]
	v_pk_add_f32 v[202:203], v[202:203], s[24:25]
	v_rcp_f32_e32 v200, v200
	v_rcp_f32_e32 v201, v201
	v_rcp_f32_e32 v202, v202
	v_rcp_f32_e32 v203, v203
	v_pk_mul_f32 v[70:71], v[70:71], v[200:201]
	v_pk_mul_f32 v[72:73], v[72:73], v[202:203]
	v_pk_mul_f32 v[150:151], v[150:151], v[70:71]
	v_pk_mul_f32 v[152:153], v[152:153], v[72:73]
	v_pk_mul_f32 v[70:71], v[196:197], v[130:131]
	v_pk_mul_f32 v[72:73], v[198:199], v[132:133]
	v_fmac_f32_dpp v70, v130, v236 row_ror:1 row_mask:0xf bank_mask:0xf
	v_fmac_f32_dpp v71, v131, v237 row_ror:1 row_mask:0xf bank_mask:0xf
	v_fmac_f32_dpp v72, v132, v238 row_ror:1 row_mask:0xf bank_mask:0xf
	v_fmac_f32_dpp v73, v133, v239 row_ror:1 row_mask:0xf bank_mask:0xf
	v_fmac_f32_dpp v70, v130, v228 row_ror:2 row_mask:0xf bank_mask:0xf
	v_fmac_f32_dpp v71, v131, v229 row_ror:2 row_mask:0xf bank_mask:0xf
	v_fmac_f32_dpp v72, v132, v230 row_ror:2 row_mask:0xf bank_mask:0xf
	v_fmac_f32_dpp v73, v133, v231 row_ror:2 row_mask:0xf bank_mask:0xf
	v_pk_mul_f32 v[200:201], v[70:71], s[14:15]
	v_pk_mul_f32 v[202:203], v[72:73], s[14:15]
	v_exp_f32_e32 v200, v200
	v_exp_f32_e32 v201, v201
	v_exp_f32_e32 v202, v202
	v_exp_f32_e32 v203, v203
	v_pk_add_f32 v[200:201], v[200:201], s[24:25]
	v_pk_add_f32 v[202:203], v[202:203], s[24:25]
	v_rcp_f32_e32 v200, v200
	v_rcp_f32_e32 v201, v201
	v_rcp_f32_e32 v202, v202
	v_rcp_f32_e32 v203, v203
	v_pk_mul_f32 v[70:71], v[70:71], v[200:201]
	v_pk_mul_f32 v[72:73], v[72:73], v[202:203]
	v_pk_mul_f32 v[146:147], v[146:147], v[70:71]
	v_pk_mul_f32 v[148:149], v[148:149], v[72:73]
	v_cvt_pk_bf16_f32 v150, v150, v151
	v_cvt_pk_bf16_f32 v151, v152, v153
	v_cvt_pk_bf16_f32 v152, v146, v147
	v_cvt_pk_bf16_f32 v153, v148, v149
	s_and_b64 exec, s[22:23], s[40:41]
	global_store_dwordx4 v[170:171], v[150:153], off
	s_mov_b64 exec, s[22:23]
	v_cndmask_b32_e64 v200, v138, v142, s[16:17]
	v_cndmask_b32_e64 v201, v139, v143, s[16:17]
	v_cndmask_b32_e64 v202, v140, v144, s[16:17]
	v_cndmask_b32_e64 v203, v141, v145, s[16:17]
	v_cndmask_b32_e64 v204, v138, v142, s[42:43]
	v_cndmask_b32_e64 v205, v139, v143, s[42:43]
	v_cndmask_b32_e64 v206, v140, v144, s[42:43]
	v_cndmask_b32_e64 v207, v141, v145, s[42:43]
	v_pk_mul_f32 v[70:71], v[192:193], v[138:139]
	v_pk_mul_f32 v[72:73], v[194:195], v[140:141]
	v_fmac_f32_dpp v70, v200, v232 row_ror:1 row_mask:0xf bank_mask:0xf
	v_fmac_f32_dpp v71, v201, v233 row_ror:1 row_mask:0xf bank_mask:0xf
	v_fmac_f32_dpp v72, v202, v234 row_ror:1 row_mask:0xf bank_mask:0xf
	v_fmac_f32_dpp v73, v203, v235 row_ror:1 row_mask:0xf bank_mask:0xf
	v_fmac_f32_dpp v70, v204, v224 row_ror:2 row_mask:0xf bank_mask:0xf
	v_fmac_f32_dpp v71, v205, v225 row_ror:2 row_mask:0xf bank_mask:0xf
	v_fmac_f32_dpp v72, v206, v226 row_ror:2 row_mask:0xf bank_mask:0xf
	v_fmac_f32_dpp v73, v207, v227 row_ror:2 row_mask:0xf bank_mask:0xf
	v_pk_mul_f32 v[200:201], v[70:71], s[14:15]
	v_pk_mul_f32 v[202:203], v[72:73], s[14:15]
	v_exp_f32_e32 v200, v200
	v_exp_f32_e32 v201, v201
; __device__ __forceinline__ float sigmoidf_(float x) { return __builtin_amdgcn_rcpf(1.0f + __expf(-x)); }
;     __device__ __forceinline__ void operator()(const f32x4 (&acc)[2][2][4][2], const Unit& u, int wr, int wc, int fr, int fq) const {
;     ...
;             for (int m = 0; m < 4; ++m) {
;                 const size_t row = (size_t)(u.pm * BM + ai * HALF + wr * 64 + m * 16 + fr);
;                 float hg[8];
; #pragma unroll
;                 for (int n = 0; n < 2; ++n)
; #pragma unroll
;                     for (int i = 0; i < 4; ++i) {
;                         const float cur = acc[ai][0][m][n][i], prv = (m > 0) ? acc[ai][0][m > 0 ? m - 1 : 0][n][i] : cur;
;                         const float r1c = dpp_ror1(cur), r1p = dpp_ror1(prv), r2c = dpp_ror2(cur), r2p = dpp_ror2(prv);
;                         const float tm1 = f1 ? r1c : r1p, tm2 = f2 ? r2c : r2p;
;                         const float cv = w0[n][i] * tm2 + w1[n][i] * tm1 + w2[n][i] * cur;
;                         hg[4 * n + i] = cv * sigmoidf_(cv) * acc[ai][1][m][n][i];
;                     }
;                 if (m == 0 && fr < 2) {
;                     const f32x4 a0 = acc[ai][0][0][0], a1 = acc[ai][0][0][1], v0 = acc[ai][1][0][0], v1 = acc[ai][1][0][1];
;                     u32x4 wa, wv; wa.x = cvt_pk_bf16(a0[0], a0[1]); wa.y = cvt_pk_bf16(a0[2], a0[3]); wa.z = cvt_pk_bf16(a1[0], a1[1]); wa.w = cvt_pk_bf16(a1[2], a1[3]);
;                     wv.x = cvt_pk_bf16(v0[0], v0[1]); wv.y = cvt_pk_bf16(v0[2], v0[3]); wv.z = cvt_pk_bf16(v1[0], v1[1]); wv.w = cvt_pk_bf16(v1[2], v1[3]);
;                     *(u32x4*)(side + ((size_t)blk * 6 + 2 + fr) * ldh + ch0) = wa; *(u32x4*)(side + ((size_t)blk * 6 + 4 + fr) * ldh + ch0) = wv;
;                 } else {
;                     u32x4 w; w.x = cvt_pk_bf16(hg[0], hg[1]); w.y = cvt_pk_bf16(hg[2], hg[3]); w.z = cvt_pk_bf16(hg[4], hg[5]); w.w = cvt_pk_bf16(hg[6], hg[7]);
;                     *(u32x4*)(HG + row * ldh + ch0) = w;
;                 }
;                 if (m == 3 && fr >= 14) {
;                     const f32x4 a0 = acc[ai][0][3][0], a1 = acc[ai][0][3][1];
;                     u32x4 wa; wa.x = cvt_pk_bf16(a0[0], a0[1]); wa.y = cvt_pk_bf16(a0[2], a0[3]); wa.z = cvt_pk_bf16(a1[0], a1[1]); wa.w = cvt_pk_bf16(a1[2], a1[3]);
;                     *(u32x4*)(side + ((size_t)blk * 6 + (fr - 14)) * ldh + ch0) = wa;
;                 }
	v_exp_f32_e32 v202, v202
	v_exp_f32_e32 v203, v203
	v_pk_add_f32 v[200:201], v[200:201], s[24:25]
	v_pk_add_f32 v[202:203], v[202:203], s[24:25]
	v_rcp_f32_e32 v200, v200
	v_rcp_f32_e32 v201, v201
	v_rcp_f32_e32 v202, v202
	v_rcp_f32_e32 v203, v203
	v_pk_mul_f32 v[70:71], v[70:71], v[200:201]
	v_pk_mul_f32 v[72:73], v[72:73], v[202:203]
	v_pk_mul_f32 v[134:135], v[134:135], v[70:71]
	v_pk_mul_f32 v[136:137], v[136:137], v[72:73]
	v_cndmask_b32_e64 v200, v126, v130, s[16:17]
	v_cndmask_b32_e64 v201, v127, v131, s[16:17]
	v_cndmask_b32_e64 v202, v128, v132, s[16:17]
	v_cndmask_b32_e64 v203, v129, v133, s[16:17]
	v_cndmask_b32_e64 v204, v126, v130, s[42:43]
	v_cndmask_b32_e64 v205, v127, v131, s[42:43]
	v_cndmask_b32_e64 v206, v128, v132, s[42:43]
	v_cndmask_b32_e64 v207, v129, v133, s[42:43]
	v_pk_mul_f32 v[70:71], v[196:197], v[126:127]
	v_pk_mul_f32 v[72:73], v[198:199], v[128:129]
	v_fmac_f32_dpp v70, v200, v236 row_ror:1 row_mask:0xf bank_mask:0xf
	v_fmac_f32_dpp v71, v201, v237 row_ror:1 row_mask:0xf bank_mask:0xf
	v_fmac_f32_dpp v72, v202, v238 row_ror:1 row_mask:0xf bank_mask:0xf
	v_fmac_f32_dpp v73, v203, v239 row_ror:1 row_mask:0xf bank_mask:0xf
	v_fmac_f32_dpp v70, v204, v228 row_ror:2 row_mask:0xf bank_mask:0xf
	v_fmac_f32_dpp v71, v205, v229 row_ror:2 row_mask:0xf bank_mask:0xf
	v_fmac_f32_dpp v72, v206, v230 row_ror:2 row_mask:0xf bank_mask:0xf
	v_fmac_f32_dpp v73, v207, v231 row_ror:2 row_mask:0xf bank_mask:0xf
	v_pk_mul_f32 v[200:201], v[70:71], s[14:15]
	v_pk_mul_f32 v[202:203], v[72:73], s[14:15]
	v_exp_f32_e32 v200, v200
	v_exp_f32_e32 v201, v201
	v_exp_f32_e32 v202, v202
	v_exp_f32_e32 v203, v203
	v_pk_add_f32 v[200:201], v[200:201], s[24:25]
	v_pk_add_f32 v[202:203], v[202:203], s[24:25]
	v_rcp_f32_e32 v200, v200
	v_rcp_f32_e32 v201, v201
	v_rcp_f32_e32 v202, v202
	v_rcp_f32_e32 v203, v203
	v_pk_mul_f32 v[70:71], v[70:71], v[200:201]
	v_pk_mul_f32 v[72:73], v[72:73], v[202:203]
	v_pk_mul_f32 v[122:123], v[122:123], v[70:71]
	v_pk_mul_f32 v[124:125], v[124:125], v[72:73]
	v_cvt_pk_bf16_f32 v134, v134, v135
	v_cvt_pk_bf16_f32 v135, v136, v137
	v_cvt_pk_bf16_f32 v136, v122, v123
	v_cvt_pk_bf16_f32 v137, v124, v125
	v_add_co_u32_e32 v170, vcc, 0x56000, v170
	v_addc_co_u32_e32 v171, vcc, 0, v171, vcc
	global_store_dwordx4 v[170:171], v[134:137], off
	v_cndmask_b32_e64 v200, v118, v138, s[16:17]
	v_cndmask_b32_e64 v201, v119, v139, s[16:17]
	v_cndmask_b32_e64 v202, v120, v140, s[16:17]
	v_cndmask_b32_e64 v203, v121, v141, s[16:17]
	v_cndmask_b32_e64 v204, v118, v138, s[42:43]
	v_cndmask_b32_e64 v205, v119, v139, s[42:43]
	v_cndmask_b32_e64 v206, v120, v140, s[42:43]
	v_cndmask_b32_e64 v207, v121, v141, s[42:43]
	v_pk_mul_f32 v[70:71], v[192:193], v[118:119]
	v_pk_mul_f32 v[72:73], v[194:195], v[120:121]
	v_fmac_f32_dpp v70, v200, v232 row_ror:1 row_mask:0xf bank_mask:0xf
	v_fmac_f32_dpp v71, v201, v233 row_ror:1 row_mask:0xf bank_mask:0xf
	v_fmac_f32_dpp v72, v202, v234 row_ror:1 row_mask:0xf bank_mask:0xf
	v_fmac_f32_dpp v73, v203, v235 row_ror:1 row_mask:0xf bank_mask:0xf
	v_fmac_f32_dpp v70, v204, v224 row_ror:2 row_mask:0xf bank_mask:0xf
	v_fmac_f32_dpp v71, v205, v225 row_ror:2 row_mask:0xf bank_mask:0xf
	v_fmac_f32_dpp v72, v206, v226 row_ror:2 row_mask:0xf bank_mask:0xf
	v_fmac_f32_dpp v73, v207, v227 row_ror:2 row_mask:0xf bank_mask:0xf
	v_pk_mul_f32 v[200:201], v[70:71], s[14:15]
	v_pk_mul_f32 v[202:203], v[72:73], s[14:15]
	v_exp_f32_e32 v200, v200
	v_exp_f32_e32 v201, v201
	v_exp_f32_e32 v202, v202
	v_exp_f32_e32 v203, v203
	v_pk_add_f32 v[200:201], v[200:201], s[24:25]
	v_pk_add_f32 v[202:203], v[202:203], s[24:25]
	v_rcp_f32_e32 v200, v200
	v_rcp_f32_e32 v201, v201
	v_rcp_f32_e32 v202, v202
	v_rcp_f32_e32 v203, v203
	v_pk_mul_f32 v[70:71], v[70:71], v[200:201]
	v_pk_mul_f32 v[72:73], v[72:73], v[202:203]
	v_pk_mul_f32 v[114:115], v[114:115], v[70:71]
	v_pk_mul_f32 v[116:117], v[116:117], v[72:73]
	v_cndmask_b32_e64 v200, v110, v126, s[16:17]
	v_cndmask_b32_e64 v201, v111, v127, s[16:17]
	v_cndmask_b32_e64 v202, v112, v128, s[16:17]
	v_cndmask_b32_e64 v203, v113, v129, s[16:17]
	v_cndmask_b32_e64 v204, v110, v126, s[42:43]
	v_cndmask_b32_e64 v205, v111, v127, s[42:43]
	v_cndmask_b32_e64 v206, v112, v128, s[42:43]
	v_cndmask_b32_e64 v207, v113, v129, s[42:43]
	v_pk_mul_f32 v[70:71], v[196:197], v[110:111]
	v_pk_mul_f32 v[72:73], v[198:199], v[112:113]
	v_fmac_f32_dpp v70, v200, v236 row_ror:1 row_mask:0xf bank_mask:0xf
	v_fmac_f32_dpp v71, v201, v237 row_ror:1 row_mask:0xf bank_mask:0xf
	v_fmac_f32_dpp v72, v202, v238 row_ror:1 row_mask:0xf bank_mask:0xf
	v_fmac_f32_dpp v73, v203, v239 row_ror:1 row_mask:0xf bank_mask:0xf
	v_fmac_f32_dpp v70, v204, v228 row_ror:2 row_mask:0xf bank_mask:0xf
	v_fmac_f32_dpp v71, v205, v229 row_ror:2 row_mask:0xf bank_mask:0xf
	v_fmac_f32_dpp v72, v206, v230 row_ror:2 row_mask:0xf bank_mask:0xf
	v_fmac_f32_dpp v73, v207, v231 row_ror:2 row_mask:0xf bank_mask:0xf
	v_pk_mul_f32 v[200:201], v[70:71], s[14:15]
	v_pk_mul_f32 v[202:203], v[72:73], s[14:15]
	v_exp_f32_e32 v200, v200
	v_exp_f32_e32 v201, v201
	v_exp_f32_e32 v202, v202
	v_exp_f32_e32 v203, v203
	v_pk_add_f32 v[200:201], v[200:201], s[24:25]
	v_pk_add_f32 v[202:203], v[202:203], s[24:25]
	v_rcp_f32_e32 v200, v200
	v_rcp_f32_e32 v201, v201
	v_rcp_f32_e32 v202, v202
	v_rcp_f32_e32 v203, v203
	v_pk_mul_f32 v[70:71], v[70:71], v[200:201]
	v_pk_mul_f32 v[72:73], v[72:73], v[202:203]
	v_pk_mul_f32 v[106:107], v[106:107], v[70:71]
	v_pk_mul_f32 v[108:109], v[108:109], v[72:73]
	v_cvt_pk_bf16_f32 v114, v114, v115
	v_cvt_pk_bf16_f32 v115, v116, v117
	v_cvt_pk_bf16_f32 v116, v106, v107
	v_cvt_pk_bf16_f32 v117, v108, v109
; __device__ __forceinline__ float sigmoidf_(float x) { return __builtin_amdgcn_rcpf(1.0f + __expf(-x)); }
;     __device__ __forceinline__ void operator()(const f32x4 (&acc)[2][2][4][2], const Unit& u, int wr, int wc, int fr, int fq) const {
;     ...
;             for (int m = 0; m < 4; ++m) {
;                 const size_t row = (size_t)(u.pm * BM + ai * HALF + wr * 64 + m * 16 + fr);
;                 float hg[8];
; #pragma unroll
;                 for (int n = 0; n < 2; ++n)
; #pragma unroll
;                     for (int i = 0; i < 4; ++i) {
;                         const float cur = acc[ai][0][m][n][i], prv = (m > 0) ? acc[ai][0][m > 0 ? m - 1 : 0][n][i] : cur;
;                         const float r1c = dpp_ror1(cur), r1p = dpp_ror1(prv), r2c = dpp_ror2(cur), r2p = dpp_ror2(prv);
;                         const float tm1 = f1 ? r1c : r1p, tm2 = f2 ? r2c : r2p;
;                         const float cv = w0[n][i] * tm2 + w1[n][i] * tm1 + w2[n][i] * cur;
;                         hg[4 * n + i] = cv * sigmoidf_(cv) * acc[ai][1][m][n][i];
;                     }
;                 if (m == 0 && fr < 2) {
;                     const f32x4 a0 = acc[ai][0][0][0], a1 = acc[ai][0][0][1], v0 = acc[ai][1][0][0], v1 = acc[ai][1][0][1];
;                     u32x4 wa, wv; wa.x = cvt_pk_bf16(a0[0], a0[1]); wa.y = cvt_pk_bf16(a0[2], a0[3]); wa.z = cvt_pk_bf16(a1[0], a1[1]); wa.w = cvt_pk_bf16(a1[2], a1[3]);
;                     wv.x = cvt_pk_bf16(v0[0], v0[1]); wv.y = cvt_pk_bf16(v0[2], v0[3]); wv.z = cvt_pk_bf16(v1[0], v1[1]); wv.w = cvt_pk_bf16(v1[2], v1[3]);
;                     *(u32x4*)(side + ((size_t)blk * 6 + 2 + fr) * ldh + ch0) = wa; *(u32x4*)(side + ((size_t)blk * 6 + 4 + fr) * ldh + ch0) = wv;
;                 } else {
;                     u32x4 w; w.x = cvt_pk_bf16(hg[0], hg[1]); w.y = cvt_pk_bf16(hg[2], hg[3]); w.z = cvt_pk_bf16(hg[4], hg[5]); w.w = cvt_pk_bf16(hg[6], hg[7]);
;                     *(u32x4*)(HG + row * ldh + ch0) = w;
;                 }
;                 if (m == 3 && fr >= 14) {
;                     const f32x4 a0 = acc[ai][0][3][0], a1 = acc[ai][0][3][1];
;                     u32x4 wa; wa.x = cvt_pk_bf16(a0[0], a0[1]); wa.y = cvt_pk_bf16(a0[2], a0[3]); wa.z = cvt_pk_bf16(a1[0], a1[1]); wa.w = cvt_pk_bf16(a1[2], a1[3]);
;                     *(u32x4*)(side + ((size_t)blk * 6 + (fr - 14)) * ldh + ch0) = wa;
;                 }
	v_add_co_u32_e32 v170, vcc, 0x56000, v170
	v_addc_co_u32_e32 v171, vcc, 0, v171, vcc
	global_store_dwordx4 v[170:171], v[114:117], off
	v_cndmask_b32_e64 v200, v98, v118, s[16:17]
	v_cndmask_b32_e64 v201, v99, v119, s[16:17]
	v_cndmask_b32_e64 v202, v100, v120, s[16:17]
	v_cndmask_b32_e64 v203, v101, v121, s[16:17]
	v_cndmask_b32_e64 v204, v98, v118, s[42:43]
	v_cndmask_b32_e64 v205, v99, v119, s[42:43]
	v_cndmask_b32_e64 v206, v100, v120, s[42:43]
	v_cndmask_b32_e64 v207, v101, v121, s[42:43]
	v_pk_mul_f32 v[70:71], v[192:193], v[98:99]
	v_pk_mul_f32 v[72:73], v[194:195], v[100:101]
	v_fmac_f32_dpp v70, v200, v232 row_ror:1 row_mask:0xf bank_mask:0xf
	v_fmac_f32_dpp v71, v201, v233 row_ror:1 row_mask:0xf bank_mask:0xf
	v_fmac_f32_dpp v72, v202, v234 row_ror:1 row_mask:0xf bank_mask:0xf
	v_fmac_f32_dpp v73, v203, v235 row_ror:1 row_mask:0xf bank_mask:0xf
	v_fmac_f32_dpp v70, v204, v224 row_ror:2 row_mask:0xf bank_mask:0xf
	v_fmac_f32_dpp v71, v205, v225 row_ror:2 row_mask:0xf bank_mask:0xf
	v_fmac_f32_dpp v72, v206, v226 row_ror:2 row_mask:0xf bank_mask:0xf
	v_fmac_f32_dpp v73, v207, v227 row_ror:2 row_mask:0xf bank_mask:0xf
	v_pk_mul_f32 v[200:201], v[70:71], s[14:15]
	v_pk_mul_f32 v[202:203], v[72:73], s[14:15]
	v_exp_f32_e32 v200, v200
	v_exp_f32_e32 v201, v201
	v_exp_f32_e32 v202, v202
	v_exp_f32_e32 v203, v203
	v_pk_add_f32 v[200:201], v[200:201], s[24:25]
	v_pk_add_f32 v[202:203], v[202:203], s[24:25]
	v_rcp_f32_e32 v200, v200
	v_rcp_f32_e32 v201, v201
	v_rcp_f32_e32 v202, v202
	v_rcp_f32_e32 v203, v203
	v_pk_mul_f32 v[70:71], v[70:71], v[200:201]
	v_pk_mul_f32 v[72:73], v[72:73], v[202:203]
	v_pk_mul_f32 v[102:103], v[102:103], v[70:71]
	v_pk_mul_f32 v[104:105], v[104:105], v[72:73]
	v_cndmask_b32_e64 v200, v94, v110, s[16:17]
	v_cndmask_b32_e64 v201, v95, v111, s[16:17]
	v_cndmask_b32_e64 v202, v96, v112, s[16:17]
	v_cndmask_b32_e64 v203, v97, v113, s[16:17]
	v_cndmask_b32_e64 v204, v94, v110, s[42:43]
	v_cndmask_b32_e64 v205, v95, v111, s[42:43]
	v_cndmask_b32_e64 v206, v96, v112, s[42:43]
	v_cndmask_b32_e64 v207, v97, v113, s[42:43]
	v_pk_mul_f32 v[70:71], v[196:197], v[94:95]
	v_pk_mul_f32 v[72:73], v[198:199], v[96:97]
	v_fmac_f32_dpp v70, v200, v236 row_ror:1 row_mask:0xf bank_mask:0xf
	v_fmac_f32_dpp v71, v201, v237 row_ror:1 row_mask:0xf bank_mask:0xf
	v_fmac_f32_dpp v72, v202, v238 row_ror:1 row_mask:0xf bank_mask:0xf
	v_fmac_f32_dpp v73, v203, v239 row_ror:1 row_mask:0xf bank_mask:0xf
	v_fmac_f32_dpp v70, v204, v228 row_ror:2 row_mask:0xf bank_mask:0xf
	v_fmac_f32_dpp v71, v205, v229 row_ror:2 row_mask:0xf bank_mask:0xf
	v_fmac_f32_dpp v72, v206, v230 row_ror:2 row_mask:0xf bank_mask:0xf
	v_fmac_f32_dpp v73, v207, v231 row_ror:2 row_mask:0xf bank_mask:0xf
	v_pk_mul_f32 v[200:201], v[70:71], s[14:15]
	v_pk_mul_f32 v[202:203], v[72:73], s[14:15]
	v_exp_f32_e32 v200, v200
	v_exp_f32_e32 v201, v201
	v_exp_f32_e32 v202, v202
	v_exp_f32_e32 v203, v203
	v_pk_add_f32 v[200:201], v[200:201], s[24:25]
	v_pk_add_f32 v[202:203], v[202:203], s[24:25]
	v_rcp_f32_e32 v200, v200
	v_rcp_f32_e32 v201, v201
	v_rcp_f32_e32 v202, v202
	v_rcp_f32_e32 v203, v203
	v_pk_mul_f32 v[70:71], v[70:71], v[200:201]
	v_pk_mul_f32 v[72:73], v[72:73], v[202:203]
	v_pk_mul_f32 v[90:91], v[90:91], v[70:71]
	v_pk_mul_f32 v[92:93], v[92:93], v[72:73]
	v_cvt_pk_bf16_f32 v102, v102, v103
	v_cvt_pk_bf16_f32 v103, v104, v105
	v_cvt_pk_bf16_f32 v104, v90, v91
	v_cvt_pk_bf16_f32 v105, v92, v93
	v_add_co_u32_e32 v170, vcc, 0x56000, v170
	v_addc_co_u32_e32 v171, vcc, 0, v171, vcc
	global_store_dwordx4 v[170:171], v[102:105], off
	v_cvt_pk_bf16_f32 v154, v98, v99
	v_cvt_pk_bf16_f32 v155, v100, v101
	v_cvt_pk_bf16_f32 v156, v94, v95
	v_cvt_pk_bf16_f32 v157, v96, v97
	v_add_co_u32_e32 v188, vcc, 0xfffb4c00, v190
	v_addc_co_u32_e32 v189, vcc, -1, v191, vcc
	s_and_b64 exec, s[22:23], s[42:43]
	global_store_dwordx4 v[188:189], v[154:157], off
	s_mov_b64 exec, s[22:23]
	v_cvt_pk_bf16_f32 v154, v62, v63
	v_cvt_pk_bf16_f32 v155, v64, v65
	v_cvt_pk_bf16_f32 v156, v42, v43
	v_cvt_pk_bf16_f32 v157, v44, v45
	v_cvt_pk_bf16_f32 v204, v82, v83
	v_cvt_pk_bf16_f32 v205, v84, v85
	v_cvt_pk_bf16_f32 v206, v78, v79
	v_cvt_pk_bf16_f32 v207, v80, v81
	v_add_co_u32_e32 v188, vcc, 0x4b400, v190
	v_addc_co_u32_e32 v189, vcc, 0, v191, vcc
	v_add_co_u32_e32 v208, vcc, 0x56000, v190
	v_addc_co_u32_e32 v209, vcc, 0, v191, vcc
	s_andn2_b64 exec, s[22:23], s[40:41]
	global_store_dwordx4 v[188:189], v[154:157], off
	global_store_dwordx4 v[208:209], v[204:207], off
	s_mov_b64 exec, s[22:23]
	s_nop 4
	v_pk_mul_f32 v[70:71], v[192:193], v[62:63]
	v_pk_mul_f32 v[72:73], v[194:195], v[64:65]
	v_fmac_f32_dpp v70, v62, v232 row_ror:1 row_mask:0xf bank_mask:0xf
	v_fmac_f32_dpp v71, v63, v233 row_ror:1 row_mask:0xf bank_mask:0xf
	v_fmac_f32_dpp v72, v64, v234 row_ror:1 row_mask:0xf bank_mask:0xf
	v_fmac_f32_dpp v73, v65, v235 row_ror:1 row_mask:0xf bank_mask:0xf
	v_fmac_f32_dpp v70, v62, v224 row_ror:2 row_mask:0xf bank_mask:0xf
	v_fmac_f32_dpp v71, v63, v225 row_ror:2 row_mask:0xf bank_mask:0xf
	v_fmac_f32_dpp v72, v64, v226 row_ror:2 row_mask:0xf bank_mask:0xf
	v_fmac_f32_dpp v73, v65, v227 row_ror:2 row_mask:0xf bank_mask:0xf
	v_pk_mul_f32 v[200:201], v[70:71], s[14:15]
	v_pk_mul_f32 v[202:203], v[72:73], s[14:15]
	v_exp_f32_e32 v200, v200
	v_exp_f32_e32 v201, v201
	v_exp_f32_e32 v202, v202
	v_exp_f32_e32 v203, v203
	v_pk_add_f32 v[200:201], v[200:201], s[24:25]
	v_pk_add_f32 v[202:203], v[202:203], s[24:25]
	v_rcp_f32_e32 v200, v200
	v_rcp_f32_e32 v201, v201
	v_rcp_f32_e32 v202, v202
	v_rcp_f32_e32 v203, v203
	v_pk_mul_f32 v[70:71], v[70:71], v[200:201]
	v_pk_mul_f32 v[72:73], v[72:73], v[202:203]
; __device__ __forceinline__ float sigmoidf_(float x) { return __builtin_amdgcn_rcpf(1.0f + __expf(-x)); }
;     __device__ __forceinline__ void operator()(const f32x4 (&acc)[2][2][4][2], const Unit& u, int wr, int wc, int fr, int fq) const {
;     ...
;             for (int m = 0; m < 4; ++m) {
;                 const size_t row = (size_t)(u.pm * BM + ai * HALF + wr * 64 + m * 16 + fr);
;                 float hg[8];
; #pragma unroll
;                 for (int n = 0; n < 2; ++n)
; #pragma unroll
;                     for (int i = 0; i < 4; ++i) {
;                         const float cur = acc[ai][0][m][n][i], prv = (m > 0) ? acc[ai][0][m > 0 ? m - 1 : 0][n][i] : cur;
;                         const float r1c = dpp_ror1(cur), r1p = dpp_ror1(prv), r2c = dpp_ror2(cur), r2p = dpp_ror2(prv);
;                         const float tm1 = f1 ? r1c : r1p, tm2 = f2 ? r2c : r2p;
;                         const float cv = w0[n][i] * tm2 + w1[n][i] * tm1 + w2[n][i] * cur;
;                         hg[4 * n + i] = cv * sigmoidf_(cv) * acc[ai][1][m][n][i];
;                     }
;                 if (m == 0 && fr < 2) {
;                     const f32x4 a0 = acc[ai][0][0][0], a1 = acc[ai][0][0][1], v0 = acc[ai][1][0][0], v1 = acc[ai][1][0][1];
;                     u32x4 wa, wv; wa.x = cvt_pk_bf16(a0[0], a0[1]); wa.y = cvt_pk_bf16(a0[2], a0[3]); wa.z = cvt_pk_bf16(a1[0], a1[1]); wa.w = cvt_pk_bf16(a1[2], a1[3]);
;                     wv.x = cvt_pk_bf16(v0[0], v0[1]); wv.y = cvt_pk_bf16(v0[2], v0[3]); wv.z = cvt_pk_bf16(v1[0], v1[1]); wv.w = cvt_pk_bf16(v1[2], v1[3]);
;                     *(u32x4*)(side + ((size_t)blk * 6 + 2 + fr) * ldh + ch0) = wa; *(u32x4*)(side + ((size_t)blk * 6 + 4 + fr) * ldh + ch0) = wv;
;                 } else {
;                     u32x4 w; w.x = cvt_pk_bf16(hg[0], hg[1]); w.y = cvt_pk_bf16(hg[2], hg[3]); w.z = cvt_pk_bf16(hg[4], hg[5]); w.w = cvt_pk_bf16(hg[6], hg[7]);
;                     *(u32x4*)(HG + row * ldh + ch0) = w;
;                 }
;                 if (m == 3 && fr >= 14) {
;                     const f32x4 a0 = acc[ai][0][3][0], a1 = acc[ai][0][3][1];
;                     u32x4 wa; wa.x = cvt_pk_bf16(a0[0], a0[1]); wa.y = cvt_pk_bf16(a0[2], a0[3]); wa.z = cvt_pk_bf16(a1[0], a1[1]); wa.w = cvt_pk_bf16(a1[2], a1[3]);
;                     *(u32x4*)(side + ((size_t)blk * 6 + (fr - 14)) * ldh + ch0) = wa;
;                 }
	v_pk_mul_f32 v[82:83], v[82:83], v[70:71]
	v_pk_mul_f32 v[84:85], v[84:85], v[72:73]
	v_pk_mul_f32 v[70:71], v[196:197], v[42:43]
	v_pk_mul_f32 v[72:73], v[198:199], v[44:45]
	v_fmac_f32_dpp v70, v42, v236 row_ror:1 row_mask:0xf bank_mask:0xf
	v_fmac_f32_dpp v71, v43, v237 row_ror:1 row_mask:0xf bank_mask:0xf
	v_fmac_f32_dpp v72, v44, v238 row_ror:1 row_mask:0xf bank_mask:0xf
	v_fmac_f32_dpp v73, v45, v239 row_ror:1 row_mask:0xf bank_mask:0xf
	v_fmac_f32_dpp v70, v42, v228 row_ror:2 row_mask:0xf bank_mask:0xf
	v_fmac_f32_dpp v71, v43, v229 row_ror:2 row_mask:0xf bank_mask:0xf
	v_fmac_f32_dpp v72, v44, v230 row_ror:2 row_mask:0xf bank_mask:0xf
	v_fmac_f32_dpp v73, v45, v231 row_ror:2 row_mask:0xf bank_mask:0xf
	v_pk_mul_f32 v[200:201], v[70:71], s[14:15]
	v_pk_mul_f32 v[202:203], v[72:73], s[14:15]
	v_exp_f32_e32 v200, v200
	v_exp_f32_e32 v201, v201
	v_exp_f32_e32 v202, v202
	v_exp_f32_e32 v203, v203
	v_pk_add_f32 v[200:201], v[200:201], s[24:25]
	v_pk_add_f32 v[202:203], v[202:203], s[24:25]
	v_rcp_f32_e32 v200, v200
	v_rcp_f32_e32 v201, v201
	v_rcp_f32_e32 v202, v202
	v_rcp_f32_e32 v203, v203
	v_pk_mul_f32 v[70:71], v[70:71], v[200:201]
	v_pk_mul_f32 v[72:73], v[72:73], v[202:203]
	v_pk_mul_f32 v[78:79], v[78:79], v[70:71]
	v_pk_mul_f32 v[80:81], v[80:81], v[72:73]
	v_cvt_pk_bf16_f32 v82, v82, v83
	v_cvt_pk_bf16_f32 v83, v84, v85
	v_cvt_pk_bf16_f32 v84, v78, v79
	v_cvt_pk_bf16_f32 v85, v80, v81
	v_add_co_u32_e32 v170, vcc, 0x1ae000, v170
	v_addc_co_u32_e32 v171, vcc, 0, v171, vcc
	s_and_b64 exec, s[22:23], s[40:41]
	global_store_dwordx4 v[170:171], v[82:85], off
	s_mov_b64 exec, s[22:23]
	v_cndmask_b32_e64 v200, v58, v62, s[16:17]
	v_cndmask_b32_e64 v201, v59, v63, s[16:17]
	v_cndmask_b32_e64 v202, v60, v64, s[16:17]
	v_cndmask_b32_e64 v203, v61, v65, s[16:17]
	v_cndmask_b32_e64 v204, v58, v62, s[42:43]
	v_cndmask_b32_e64 v205, v59, v63, s[42:43]
	v_cndmask_b32_e64 v206, v60, v64, s[42:43]
	v_cndmask_b32_e64 v207, v61, v65, s[42:43]
	v_pk_mul_f32 v[70:71], v[192:193], v[58:59]
	v_pk_mul_f32 v[72:73], v[194:195], v[60:61]
	v_fmac_f32_dpp v70, v200, v232 row_ror:1 row_mask:0xf bank_mask:0xf
	v_fmac_f32_dpp v71, v201, v233 row_ror:1 row_mask:0xf bank_mask:0xf
	v_fmac_f32_dpp v72, v202, v234 row_ror:1 row_mask:0xf bank_mask:0xf
	v_fmac_f32_dpp v73, v203, v235 row_ror:1 row_mask:0xf bank_mask:0xf
	v_fmac_f32_dpp v70, v204, v224 row_ror:2 row_mask:0xf bank_mask:0xf
	v_fmac_f32_dpp v71, v205, v225 row_ror:2 row_mask:0xf bank_mask:0xf
	v_fmac_f32_dpp v72, v206, v226 row_ror:2 row_mask:0xf bank_mask:0xf
	v_fmac_f32_dpp v73, v207, v227 row_ror:2 row_mask:0xf bank_mask:0xf
	v_pk_mul_f32 v[200:201], v[70:71], s[14:15]
	v_pk_mul_f32 v[202:203], v[72:73], s[14:15]
	v_exp_f32_e32 v200, v200
	v_exp_f32_e32 v201, v201
	v_exp_f32_e32 v202, v202
	v_exp_f32_e32 v203, v203
	v_pk_add_f32 v[200:201], v[200:201], s[24:25]
	v_pk_add_f32 v[202:203], v[202:203], s[24:25]
	v_rcp_f32_e32 v200, v200
	v_rcp_f32_e32 v201, v201
	v_rcp_f32_e32 v202, v202
	v_rcp_f32_e32 v203, v203
	v_pk_mul_f32 v[70:71], v[70:71], v[200:201]
	v_pk_mul_f32 v[72:73], v[72:73], v[202:203]
	v_pk_mul_f32 v[46:47], v[46:47], v[70:71]
	v_pk_mul_f32 v[48:49], v[48:49], v[72:73]
	v_cndmask_b32_e64 v200, v38, v42, s[16:17]
	v_cndmask_b32_e64 v201, v39, v43, s[16:17]
	v_cndmask_b32_e64 v202, v40, v44, s[16:17]
	v_cndmask_b32_e64 v203, v41, v45, s[16:17]
	v_cndmask_b32_e64 v204, v38, v42, s[42:43]
	v_cndmask_b32_e64 v205, v39, v43, s[42:43]
	v_cndmask_b32_e64 v206, v40, v44, s[42:43]
	v_cndmask_b32_e64 v207, v41, v45, s[42:43]
	v_pk_mul_f32 v[70:71], v[196:197], v[38:39]
	v_pk_mul_f32 v[72:73], v[198:199], v[40:41]
	v_fmac_f32_dpp v70, v200, v236 row_ror:1 row_mask:0xf bank_mask:0xf
	v_fmac_f32_dpp v71, v201, v237 row_ror:1 row_mask:0xf bank_mask:0xf
	v_fmac_f32_dpp v72, v202, v238 row_ror:1 row_mask:0xf bank_mask:0xf
	v_fmac_f32_dpp v73, v203, v239 row_ror:1 row_mask:0xf bank_mask:0xf
	v_fmac_f32_dpp v70, v204, v228 row_ror:2 row_mask:0xf bank_mask:0xf
	v_fmac_f32_dpp v71, v205, v229 row_ror:2 row_mask:0xf bank_mask:0xf
	v_fmac_f32_dpp v72, v206, v230 row_ror:2 row_mask:0xf bank_mask:0xf
	v_fmac_f32_dpp v73, v207, v231 row_ror:2 row_mask:0xf bank_mask:0xf
	v_pk_mul_f32 v[200:201], v[70:71], s[14:15]
	v_pk_mul_f32 v[202:203], v[72:73], s[14:15]
	v_exp_f32_e32 v200, v200
	v_exp_f32_e32 v201, v201
	v_exp_f32_e32 v202, v202
	v_exp_f32_e32 v203, v203
	v_pk_add_f32 v[200:201], v[200:201], s[24:25]
	v_pk_add_f32 v[202:203], v[202:203], s[24:25]
	v_rcp_f32_e32 v200, v200
	v_rcp_f32_e32 v201, v201
	v_rcp_f32_e32 v202, v202
	v_rcp_f32_e32 v203, v203
	v_pk_mul_f32 v[70:71], v[70:71], v[200:201]
	v_pk_mul_f32 v[72:73], v[72:73], v[202:203]
	v_pk_mul_f32 v[34:35], v[34:35], v[70:71]
	v_pk_mul_f32 v[36:37], v[36:37], v[72:73]
	v_cvt_pk_bf16_f32 v46, v46, v47
	v_cvt_pk_bf16_f32 v47, v48, v49
	v_cvt_pk_bf16_f32 v48, v34, v35
	v_cvt_pk_bf16_f32 v49, v36, v37
	v_add_co_u32_e32 v170, vcc, 0x56000, v170
	v_addc_co_u32_e32 v171, vcc, 0, v171, vcc
	global_store_dwordx4 v[170:171], v[46:49], off
	v_cndmask_b32_e64 v200, v30, v58, s[16:17]
	v_cndmask_b32_e64 v201, v31, v59, s[16:17]
	v_cndmask_b32_e64 v202, v32, v60, s[16:17]
	v_cndmask_b32_e64 v203, v33, v61, s[16:17]
	v_cndmask_b32_e64 v204, v30, v58, s[42:43]
	v_cndmask_b32_e64 v205, v31, v59, s[42:43]
	v_cndmask_b32_e64 v206, v32, v60, s[42:43]
	v_cndmask_b32_e64 v207, v33, v61, s[42:43]
	v_pk_mul_f32 v[70:71], v[192:193], v[30:31]
	v_pk_mul_f32 v[72:73], v[194:195], v[32:33]
	v_fmac_f32_dpp v70, v200, v232 row_ror:1 row_mask:0xf bank_mask:0xf
	v_fmac_f32_dpp v71, v201, v233 row_ror:1 row_mask:0xf bank_mask:0xf
	v_fmac_f32_dpp v72, v202, v234 row_ror:1 row_mask:0xf bank_mask:0xf
; __device__ __forceinline__ unsigned cvt_pk_bf16(float lo, float hi) { unsigned r; asm volatile("v_cvt_pk_bf16_f32 %0, %1, %2" : "=v"(r) : "v"(lo), "v"(hi)); return r; }
; __device__ __forceinline__ float sigmoidf_(float x) { return __builtin_amdgcn_rcpf(1.0f + __expf(-x)); }
;     __device__ __forceinline__ void operator()(const f32x4 (&acc)[2][2][4][2], const Unit& u, int wr, int wc, int fr, int fq) const {
;     ...
;                     for (int i = 0; i < 4; ++i) {
;                         const float cur = acc[ai][0][m][n][i], prv = (m > 0) ? acc[ai][0][m > 0 ? m - 1 : 0][n][i] : cur;
;                         const float r1c = dpp_ror1(cur), r1p = dpp_ror1(prv), r2c = dpp_ror2(cur), r2p = dpp_ror2(prv);
;                         const float tm1 = f1 ? r1c : r1p, tm2 = f2 ? r2c : r2p;
;                         const float cv = w0[n][i] * tm2 + w1[n][i] * tm1 + w2[n][i] * cur;
;                         hg[4 * n + i] = cv * sigmoidf_(cv) * acc[ai][1][m][n][i];
;                     }
;                 if (m == 0 && fr < 2) {
;                     const f32x4 a0 = acc[ai][0][0][0], a1 = acc[ai][0][0][1], v0 = acc[ai][1][0][0], v1 = acc[ai][1][0][1];
;                     u32x4 wa, wv; wa.x = cvt_pk_bf16(a0[0], a0[1]); wa.y = cvt_pk_bf16(a0[2], a0[3]); wa.z = cvt_pk_bf16(a1[0], a1[1]); wa.w = cvt_pk_bf16(a1[2], a1[3]);
;                     wv.x = cvt_pk_bf16(v0[0], v0[1]); wv.y = cvt_pk_bf16(v0[2], v0[3]); wv.z = cvt_pk_bf16(v1[0], v1[1]); wv.w = cvt_pk_bf16(v1[2], v1[3]);
;                     *(u32x4*)(side + ((size_t)blk * 6 + 2 + fr) * ldh + ch0) = wa; *(u32x4*)(side + ((size_t)blk * 6 + 4 + fr) * ldh + ch0) = wv;
;                 } else {
;                     u32x4 w; w.x = cvt_pk_bf16(hg[0], hg[1]); w.y = cvt_pk_bf16(hg[2], hg[3]); w.z = cvt_pk_bf16(hg[4], hg[5]); w.w = cvt_pk_bf16(hg[6], hg[7]);
;                     *(u32x4*)(HG + row * ldh + ch0) = w;
;                 }
;                 if (m == 3 && fr >= 14) {
;                     const f32x4 a0 = acc[ai][0][3][0], a1 = acc[ai][0][3][1];
;                     u32x4 wa; wa.x = cvt_pk_bf16(a0[0], a0[1]); wa.y = cvt_pk_bf16(a0[2], a0[3]); wa.z = cvt_pk_bf16(a1[0], a1[1]); wa.w = cvt_pk_bf16(a1[2], a1[3]);
;                     *(u32x4*)(side + ((size_t)blk * 6 + (fr - 14)) * ldh + ch0) = wa;
;                 }
	v_fmac_f32_dpp v73, v203, v235 row_ror:1 row_mask:0xf bank_mask:0xf
	v_fmac_f32_dpp v70, v204, v224 row_ror:2 row_mask:0xf bank_mask:0xf
	v_fmac_f32_dpp v71, v205, v225 row_ror:2 row_mask:0xf bank_mask:0xf
	v_fmac_f32_dpp v72, v206, v226 row_ror:2 row_mask:0xf bank_mask:0xf
	v_fmac_f32_dpp v73, v207, v227 row_ror:2 row_mask:0xf bank_mask:0xf
	v_pk_mul_f32 v[200:201], v[70:71], s[14:15]
	v_pk_mul_f32 v[202:203], v[72:73], s[14:15]
	v_exp_f32_e32 v200, v200
	v_exp_f32_e32 v201, v201
	v_exp_f32_e32 v202, v202
	v_exp_f32_e32 v203, v203
	v_pk_add_f32 v[200:201], v[200:201], s[24:25]
	v_pk_add_f32 v[202:203], v[202:203], s[24:25]
	v_rcp_f32_e32 v200, v200
	v_rcp_f32_e32 v201, v201
	v_rcp_f32_e32 v202, v202
	v_rcp_f32_e32 v203, v203
	v_pk_mul_f32 v[70:71], v[70:71], v[200:201]
	v_pk_mul_f32 v[72:73], v[72:73], v[202:203]
	v_pk_mul_f32 v[26:27], v[26:27], v[70:71]
	v_pk_mul_f32 v[28:29], v[28:29], v[72:73]
	v_cndmask_b32_e64 v200, v22, v38, s[16:17]
	v_cndmask_b32_e64 v201, v23, v39, s[16:17]
	v_cndmask_b32_e64 v202, v24, v40, s[16:17]
	v_cndmask_b32_e64 v203, v25, v41, s[16:17]
	v_cndmask_b32_e64 v204, v22, v38, s[42:43]
	v_cndmask_b32_e64 v205, v23, v39, s[42:43]
	v_cndmask_b32_e64 v206, v24, v40, s[42:43]
	v_cndmask_b32_e64 v207, v25, v41, s[42:43]
	v_pk_mul_f32 v[70:71], v[196:197], v[22:23]
	v_pk_mul_f32 v[72:73], v[198:199], v[24:25]
	v_fmac_f32_dpp v70, v200, v236 row_ror:1 row_mask:0xf bank_mask:0xf
	v_fmac_f32_dpp v71, v201, v237 row_ror:1 row_mask:0xf bank_mask:0xf
	v_fmac_f32_dpp v72, v202, v238 row_ror:1 row_mask:0xf bank_mask:0xf
	v_fmac_f32_dpp v73, v203, v239 row_ror:1 row_mask:0xf bank_mask:0xf
	v_fmac_f32_dpp v70, v204, v228 row_ror:2 row_mask:0xf bank_mask:0xf
	v_fmac_f32_dpp v71, v205, v229 row_ror:2 row_mask:0xf bank_mask:0xf
	v_fmac_f32_dpp v72, v206, v230 row_ror:2 row_mask:0xf bank_mask:0xf
	v_fmac_f32_dpp v73, v207, v231 row_ror:2 row_mask:0xf bank_mask:0xf
	v_pk_mul_f32 v[200:201], v[70:71], s[14:15]
	v_pk_mul_f32 v[202:203], v[72:73], s[14:15]
	v_exp_f32_e32 v200, v200
	v_exp_f32_e32 v201, v201
	v_exp_f32_e32 v202, v202
	v_exp_f32_e32 v203, v203
	v_pk_add_f32 v[200:201], v[200:201], s[24:25]
	v_pk_add_f32 v[202:203], v[202:203], s[24:25]
	v_rcp_f32_e32 v200, v200
	v_rcp_f32_e32 v201, v201
	v_rcp_f32_e32 v202, v202
	v_rcp_f32_e32 v203, v203
	v_pk_mul_f32 v[70:71], v[70:71], v[200:201]
	v_pk_mul_f32 v[72:73], v[72:73], v[202:203]
	v_pk_mul_f32 v[18:19], v[18:19], v[70:71]
	v_pk_mul_f32 v[20:21], v[20:21], v[72:73]
	v_cvt_pk_bf16_f32 v26, v26, v27
	v_cvt_pk_bf16_f32 v27, v28, v29
	v_cvt_pk_bf16_f32 v28, v18, v19
	v_cvt_pk_bf16_f32 v29, v20, v21
	v_add_co_u32_e32 v170, vcc, 0x56000, v170
	v_addc_co_u32_e32 v171, vcc, 0, v171, vcc
	global_store_dwordx4 v[170:171], v[26:29], off
	v_cndmask_b32_e64 v200, v10, v30, s[16:17]
	v_cndmask_b32_e64 v201, v11, v31, s[16:17]
	v_cndmask_b32_e64 v202, v12, v32, s[16:17]
	v_cndmask_b32_e64 v203, v13, v33, s[16:17]
	v_cndmask_b32_e64 v204, v10, v30, s[42:43]
	v_cndmask_b32_e64 v205, v11, v31, s[42:43]
	v_cndmask_b32_e64 v206, v12, v32, s[42:43]
	v_cndmask_b32_e64 v207, v13, v33, s[42:43]
	v_pk_mul_f32 v[70:71], v[192:193], v[10:11]
	v_pk_mul_f32 v[72:73], v[194:195], v[12:13]
	v_fmac_f32_dpp v70, v200, v232 row_ror:1 row_mask:0xf bank_mask:0xf
	v_fmac_f32_dpp v71, v201, v233 row_ror:1 row_mask:0xf bank_mask:0xf
	v_fmac_f32_dpp v72, v202, v234 row_ror:1 row_mask:0xf bank_mask:0xf
	v_fmac_f32_dpp v73, v203, v235 row_ror:1 row_mask:0xf bank_mask:0xf
	v_fmac_f32_dpp v70, v204, v224 row_ror:2 row_mask:0xf bank_mask:0xf
	v_fmac_f32_dpp v71, v205, v225 row_ror:2 row_mask:0xf bank_mask:0xf
	v_fmac_f32_dpp v72, v206, v226 row_ror:2 row_mask:0xf bank_mask:0xf
	v_fmac_f32_dpp v73, v207, v227 row_ror:2 row_mask:0xf bank_mask:0xf
	v_pk_mul_f32 v[200:201], v[70:71], s[14:15]
	v_pk_mul_f32 v[202:203], v[72:73], s[14:15]
	v_exp_f32_e32 v200, v200
	v_exp_f32_e32 v201, v201
	v_exp_f32_e32 v202, v202
	v_exp_f32_e32 v203, v203
	v_pk_add_f32 v[200:201], v[200:201], s[24:25]
	v_pk_add_f32 v[202:203], v[202:203], s[24:25]
	v_rcp_f32_e32 v200, v200
	v_rcp_f32_e32 v201, v201
	v_rcp_f32_e32 v202, v202
	v_rcp_f32_e32 v203, v203
	v_pk_mul_f32 v[70:71], v[70:71], v[200:201]
	v_pk_mul_f32 v[72:73], v[72:73], v[202:203]
	v_pk_mul_f32 v[14:15], v[14:15], v[70:71]
	v_pk_mul_f32 v[16:17], v[16:17], v[72:73]
	v_cndmask_b32_e64 v200, v6, v22, s[16:17]
	v_cndmask_b32_e64 v201, v7, v23, s[16:17]
	v_cndmask_b32_e64 v202, v8, v24, s[16:17]
	v_cndmask_b32_e64 v203, v9, v25, s[16:17]
	v_cndmask_b32_e64 v204, v6, v22, s[42:43]
	v_cndmask_b32_e64 v205, v7, v23, s[42:43]
	v_cndmask_b32_e64 v206, v8, v24, s[42:43]
	v_cndmask_b32_e64 v207, v9, v25, s[42:43]
	v_pk_mul_f32 v[70:71], v[196:197], v[6:7]
	v_pk_mul_f32 v[72:73], v[198:199], v[8:9]
	v_fmac_f32_dpp v70, v200, v236 row_ror:1 row_mask:0xf bank_mask:0xf
	v_fmac_f32_dpp v71, v201, v237 row_ror:1 row_mask:0xf bank_mask:0xf
	v_fmac_f32_dpp v72, v202, v238 row_ror:1 row_mask:0xf bank_mask:0xf
	v_fmac_f32_dpp v73, v203, v239 row_ror:1 row_mask:0xf bank_mask:0xf
	v_fmac_f32_dpp v70, v204, v228 row_ror:2 row_mask:0xf bank_mask:0xf
	v_fmac_f32_dpp v71, v205, v229 row_ror:2 row_mask:0xf bank_mask:0xf
	v_fmac_f32_dpp v72, v206, v230 row_ror:2 row_mask:0xf bank_mask:0xf
	v_fmac_f32_dpp v73, v207, v231 row_ror:2 row_mask:0xf bank_mask:0xf
	v_pk_mul_f32 v[200:201], v[70:71], s[14:15]
	v_pk_mul_f32 v[202:203], v[72:73], s[14:15]
	v_exp_f32_e32 v200, v200
	v_exp_f32_e32 v201, v201
	v_exp_f32_e32 v202, v202
	v_exp_f32_e32 v203, v203
	v_pk_add_f32 v[200:201], v[200:201], s[24:25]
	v_pk_add_f32 v[202:203], v[202:203], s[24:25]
	v_rcp_f32_e32 v200, v200
	v_rcp_f32_e32 v201, v201
	v_rcp_f32_e32 v202, v202
	v_rcp_f32_e32 v203, v203
	v_pk_mul_f32 v[70:71], v[70:71], v[200:201]
	v_pk_mul_f32 v[72:73], v[72:73], v[202:203]
	v_pk_mul_f32 v[2:3], v[2:3], v[70:71]
	v_pk_mul_f32 v[4:5], v[4:5], v[72:73]
	v_cvt_pk_bf16_f32 v14, v14, v15
	v_cvt_pk_bf16_f32 v15, v16, v17
	v_cvt_pk_bf16_f32 v16, v2, v3
	v_cvt_pk_bf16_f32 v17, v4, v5
	v_add_co_u32_e32 v170, vcc, 0x56000, v170
	v_addc_co_u32_e32 v171, vcc, 0, v171, vcc
	global_store_dwordx4 v[170:171], v[14:17], off
	v_cvt_pk_bf16_f32 v154, v10, v11
	v_cvt_pk_bf16_f32 v155, v12, v13
	v_cvt_pk_bf16_f32 v156, v6, v7
	v_cvt_pk_bf16_f32 v157, v8, v9
	v_add_co_u32_e32 v188, vcc, 0xffff5400, v190
	v_addc_co_u32_e32 v189, vcc, -1, v191, vcc
	s_and_b64 exec, s[22:23], s[42:43]
	global_store_dwordx4 v[188:189], v[154:157], off
	s_mov_b64 exec, s[22:23]
	s_andn2_b64 vcc, exec, s[20:21]
	s_mov_b64 s[20:21], -1
	s_cbranch_vccnz .LBB0_699
	s_andn2_b64 vcc, exec, s[46:47]
	s_cbranch_vccnz .LBB0_698
	s_nop 0
	s_branch .LBB0_698
